# v63 plus code placement: heads of the four big GEMM K-loops aligned to 64 bytes (.p2align 6)
# speedup vs baseline: 1.0013x; 1.0013x over previous
.LBB0_141:
	s_ashr_i32 s31, s30, 31
	s_lshl_b64 s[4:5], s[30:31], 19
	s_add_u32 s34, s66, s4
	s_addc_u32 s35, s67, s5
	s_and_b64 s[4:5], s[6:7], exec
	s_cselect_b32 s1, s35, s73
	s_cselect_b32 s4, s34, s72
	s_ashr_i32 s29, s28, 31
	s_lshl_b64 s[36:37], s[28:29], 19
	s_add_u32 s36, s18, s36
	s_addc_u32 s37, s19, s37
	s_and_b64 s[76:77], s[6:7], exec
	s_cselect_b32 s5, s37, s75
	s_cselect_b32 s9, s36, s74
	s_add_u32 s72, s72, 0x40080
	s_addc_u32 s73, s73, 0
	s_add_u32 s29, s74, 0x100
	v_mov_b32_e32 v2, 0
	s_addc_u32 s31, s75, 0
	s_mov_b32 s71, -2
	v_mov_b32_e32 v3, v2
	v_mov_b32_e32 v4, v2
	v_mov_b32_e32 v5, v2
	v_mov_b32_e32 v6, v2
	v_mov_b32_e32 v7, v2
	v_mov_b32_e32 v8, v2
	v_mov_b32_e32 v9, v2
	v_mov_b32_e32 v18, v2
	v_mov_b32_e32 v19, v2
	v_mov_b32_e32 v20, v2
	v_mov_b32_e32 v21, v2
	v_mov_b32_e32 v22, v2
	v_mov_b32_e32 v23, v2
	v_mov_b32_e32 v24, v2
	v_mov_b32_e32 v25, v2
	v_mov_b32_e32 v34, v2
	v_mov_b32_e32 v35, v2
	v_mov_b32_e32 v36, v2
	v_mov_b32_e32 v37, v2
	v_mov_b32_e32 v38, v2
	v_mov_b32_e32 v39, v2
	v_mov_b32_e32 v40, v2
	v_mov_b32_e32 v41, v2
	v_mov_b32_e32 v50, v2
	v_mov_b32_e32 v51, v2
	v_mov_b32_e32 v52, v2
	v_mov_b32_e32 v53, v2
	v_mov_b32_e32 v54, v2
	v_mov_b32_e32 v55, v2
	v_mov_b32_e32 v56, v2
	v_mov_b32_e32 v57, v2
	v_mov_b32_e32 v10, v2
	v_mov_b32_e32 v11, v2
	v_mov_b32_e32 v12, v2
	v_mov_b32_e32 v13, v2
	v_mov_b32_e32 v14, v2
	v_mov_b32_e32 v15, v2
	v_mov_b32_e32 v16, v2
	v_mov_b32_e32 v17, v2
	v_mov_b32_e32 v26, v2
	v_mov_b32_e32 v27, v2
	v_mov_b32_e32 v28, v2
	v_mov_b32_e32 v29, v2
	v_mov_b32_e32 v30, v2
	v_mov_b32_e32 v31, v2
	v_mov_b32_e32 v32, v2
	v_mov_b32_e32 v33, v2
	v_mov_b32_e32 v42, v2
	v_mov_b32_e32 v43, v2
	v_mov_b32_e32 v44, v2
	v_mov_b32_e32 v45, v2
	v_mov_b32_e32 v46, v2
	v_mov_b32_e32 v47, v2
	v_mov_b32_e32 v48, v2
	v_mov_b32_e32 v49, v2
	v_mov_b32_e32 v58, v2
	v_mov_b32_e32 v59, v2
	v_mov_b32_e32 v60, v2
	v_mov_b32_e32 v61, v2
	v_mov_b32_e32 v62, v2
	v_mov_b32_e32 v63, v2
	v_mov_b32_e32 v64, v2
	v_mov_b32_e32 v65, v2
	v_mov_b32_e32 v66, v2
	v_mov_b32_e32 v67, v2
	v_mov_b32_e32 v68, v2
	v_mov_b32_e32 v69, v2
	v_mov_b32_e32 v70, v2
	v_mov_b32_e32 v71, v2
	v_mov_b32_e32 v72, v2
	v_mov_b32_e32 v73, v2
	v_mov_b32_e32 v82, v2
	v_mov_b32_e32 v83, v2
	v_mov_b32_e32 v84, v2
	v_mov_b32_e32 v85, v2
	v_mov_b32_e32 v86, v2
	v_mov_b32_e32 v87, v2
	v_mov_b32_e32 v88, v2
	v_mov_b32_e32 v89, v2
	v_mov_b32_e32 v98, v2
	v_mov_b32_e32 v99, v2
	v_mov_b32_e32 v100, v2
	v_mov_b32_e32 v101, v2
	v_mov_b32_e32 v102, v2
	v_mov_b32_e32 v103, v2
	v_mov_b32_e32 v104, v2
	v_mov_b32_e32 v105, v2
	v_mov_b32_e32 v114, v2
	v_mov_b32_e32 v115, v2
	v_mov_b32_e32 v116, v2
	v_mov_b32_e32 v117, v2
	v_mov_b32_e32 v118, v2
	v_mov_b32_e32 v119, v2
	v_mov_b32_e32 v120, v2
	v_mov_b32_e32 v121, v2
	v_mov_b32_e32 v74, v2
	v_mov_b32_e32 v75, v2
	v_mov_b32_e32 v76, v2
	v_mov_b32_e32 v77, v2
	v_mov_b32_e32 v78, v2
	v_mov_b32_e32 v79, v2
	v_mov_b32_e32 v80, v2
	v_mov_b32_e32 v81, v2
	v_mov_b32_e32 v90, v2
	v_mov_b32_e32 v91, v2
	v_mov_b32_e32 v92, v2
	v_mov_b32_e32 v93, v2
	v_mov_b32_e32 v94, v2
	v_mov_b32_e32 v95, v2
	v_mov_b32_e32 v96, v2
	v_mov_b32_e32 v97, v2
	v_mov_b32_e32 v106, v2
	v_mov_b32_e32 v107, v2
	v_mov_b32_e32 v108, v2
	v_mov_b32_e32 v109, v2
	v_mov_b32_e32 v110, v2
	v_mov_b32_e32 v111, v2
	v_mov_b32_e32 v112, v2
	v_mov_b32_e32 v113, v2
	v_mov_b32_e32 v122, v2
	v_mov_b32_e32 v123, v2
	v_mov_b32_e32 v124, v2
	v_mov_b32_e32 v125, v2
	v_mov_b32_e32 v126, v2
	v_mov_b32_e32 v127, v2
	v_mov_b32_e32 v128, v2
	v_mov_b32_e32 v129, v2
	.p2align 6

.LBB0_450:
	s_add_u32 s4, s26, 0x100
	s_addc_u32 s5, s27, 0
	s_ashr_i32 s21, s20, 31
	s_lshl_b64 s[22:23], s[20:21], 19
	s_add_u32 s24, s60, s22
	s_addc_u32 s25, s61, s23
	s_and_b64 s[22:23], s[8:9], exec
	s_cselect_b32 s21, s25, s11
	s_cselect_b32 s77, s24, s10
	s_ashr_i32 s19, s18, 31
	s_lshl_b64 s[22:23], s[18:19], 19
	s_add_u32 s22, s70, s22
	s_addc_u32 s23, s71, s23
	s_and_b64 s[28:29], s[8:9], exec
	s_cselect_b32 s19, s23, s27
	s_cselect_b32 s78, s22, s26
	v_lshl_add_u64 v[146:147], s[10:11], 0, v[138:139]
	v_lshl_add_u64 v[148:149], s[10:11], 0, v[140:141]
	s_mov_b32 s79, -2
	s_mov_b64 s[26:27], 0
	.p2align 6

.LBB0_580:
	s_ashr_i32 s31, s30, 31
	s_lshl_b64 s[4:5], s[30:31], 19
	s_add_u32 s34, s66, s4
	s_addc_u32 s35, s67, s5
	s_and_b64 s[4:5], s[6:7], exec
	s_cselect_b32 s4, s35, s45
	s_cselect_b32 s5, s34, s44
	s_ashr_i32 s29, s28, 31
	s_lshl_b64 s[36:37], s[28:29], 19
	s_add_u32 s36, s88, s36
	s_addc_u32 s37, s89, s37
	s_and_b64 s[58:59], s[6:7], exec
	s_cselect_b32 s29, s37, s57
	s_cselect_b32 s31, s36, s56
	s_add_u32 s44, s44, 0x40080
	s_addc_u32 s45, s45, 0
	s_add_u32 s78, s56, 0x100
	v_mov_b32_e32 v2, 0
	s_addc_u32 s79, s57, 0
	s_mov_b32 s80, -2
	v_mov_b32_e32 v3, v2
	v_mov_b32_e32 v4, v2
	v_mov_b32_e32 v5, v2
	v_mov_b32_e32 v6, v2
	v_mov_b32_e32 v7, v2
	v_mov_b32_e32 v8, v2
	v_mov_b32_e32 v9, v2
	v_mov_b32_e32 v18, v2
	v_mov_b32_e32 v19, v2
	v_mov_b32_e32 v20, v2
	v_mov_b32_e32 v21, v2
	v_mov_b32_e32 v22, v2
	v_mov_b32_e32 v23, v2
	v_mov_b32_e32 v24, v2
	v_mov_b32_e32 v25, v2
	v_mov_b32_e32 v34, v2
	v_mov_b32_e32 v35, v2
	v_mov_b32_e32 v36, v2
	v_mov_b32_e32 v37, v2
	v_mov_b32_e32 v38, v2
	v_mov_b32_e32 v39, v2
	v_mov_b32_e32 v40, v2
	v_mov_b32_e32 v41, v2
	v_mov_b32_e32 v50, v2
	v_mov_b32_e32 v51, v2
	v_mov_b32_e32 v52, v2
	v_mov_b32_e32 v53, v2
	v_mov_b32_e32 v54, v2
	v_mov_b32_e32 v55, v2
	v_mov_b32_e32 v56, v2
	v_mov_b32_e32 v57, v2
	v_mov_b32_e32 v10, v2
	v_mov_b32_e32 v11, v2
	v_mov_b32_e32 v12, v2
	v_mov_b32_e32 v13, v2
	v_mov_b32_e32 v14, v2
	v_mov_b32_e32 v15, v2
	v_mov_b32_e32 v16, v2
	v_mov_b32_e32 v17, v2
	v_mov_b32_e32 v26, v2
	v_mov_b32_e32 v27, v2
	v_mov_b32_e32 v28, v2
	v_mov_b32_e32 v29, v2
	v_mov_b32_e32 v30, v2
	v_mov_b32_e32 v31, v2
	v_mov_b32_e32 v32, v2
	v_mov_b32_e32 v33, v2
	v_mov_b32_e32 v42, v2
	v_mov_b32_e32 v43, v2
	v_mov_b32_e32 v44, v2
	v_mov_b32_e32 v45, v2
	v_mov_b32_e32 v46, v2
	v_mov_b32_e32 v47, v2
	v_mov_b32_e32 v48, v2
	v_mov_b32_e32 v49, v2
	v_mov_b32_e32 v58, v2
	v_mov_b32_e32 v59, v2
	v_mov_b32_e32 v60, v2
	v_mov_b32_e32 v61, v2
	v_mov_b32_e32 v62, v2
	v_mov_b32_e32 v63, v2
	v_mov_b32_e32 v64, v2
	v_mov_b32_e32 v65, v2
	v_mov_b32_e32 v66, v2
	v_mov_b32_e32 v67, v2
	v_mov_b32_e32 v68, v2
	v_mov_b32_e32 v69, v2
	v_mov_b32_e32 v70, v2
	v_mov_b32_e32 v71, v2
	v_mov_b32_e32 v72, v2
	v_mov_b32_e32 v73, v2
	v_mov_b32_e32 v82, v2
	v_mov_b32_e32 v83, v2
	v_mov_b32_e32 v84, v2
	v_mov_b32_e32 v85, v2
	v_mov_b32_e32 v86, v2
	v_mov_b32_e32 v87, v2
	v_mov_b32_e32 v88, v2
	v_mov_b32_e32 v89, v2
	v_mov_b32_e32 v98, v2
	v_mov_b32_e32 v99, v2
	v_mov_b32_e32 v100, v2
	v_mov_b32_e32 v101, v2
	v_mov_b32_e32 v102, v2
	v_mov_b32_e32 v103, v2
	v_mov_b32_e32 v104, v2
	v_mov_b32_e32 v105, v2
	v_mov_b32_e32 v106, v2
	v_mov_b32_e32 v107, v2
	v_mov_b32_e32 v108, v2
	v_mov_b32_e32 v109, v2
	v_mov_b32_e32 v110, v2
	v_mov_b32_e32 v111, v2
	v_mov_b32_e32 v112, v2
	v_mov_b32_e32 v113, v2
	v_mov_b32_e32 v74, v2
	v_mov_b32_e32 v75, v2
	v_mov_b32_e32 v76, v2
	v_mov_b32_e32 v77, v2
	v_mov_b32_e32 v78, v2
	v_mov_b32_e32 v79, v2
	v_mov_b32_e32 v80, v2
	v_mov_b32_e32 v81, v2
	v_mov_b32_e32 v90, v2
	v_mov_b32_e32 v91, v2
	v_mov_b32_e32 v92, v2
	v_mov_b32_e32 v93, v2
	v_mov_b32_e32 v94, v2
	v_mov_b32_e32 v95, v2
	v_mov_b32_e32 v96, v2
	v_mov_b32_e32 v97, v2
	v_mov_b32_e32 v114, v2
	v_mov_b32_e32 v115, v2
	v_mov_b32_e32 v116, v2
	v_mov_b32_e32 v117, v2
	v_mov_b32_e32 v118, v2
	v_mov_b32_e32 v119, v2
	v_mov_b32_e32 v120, v2
	v_mov_b32_e32 v121, v2
	v_mov_b32_e32 v122, v2
	v_mov_b32_e32 v123, v2
	v_mov_b32_e32 v124, v2
	v_mov_b32_e32 v125, v2
	v_mov_b32_e32 v126, v2
	v_mov_b32_e32 v127, v2
	v_mov_b32_e32 v128, v2
	v_mov_b32_e32 v129, v2
	.p2align 6

.LBB0_648:
	s_add_u32 s60, s26, 0x100
	s_addc_u32 s61, s27, 0
	s_ashr_i32 s21, s20, 31
	s_lshl_b64 s[22:23], s[20:21], 21
	s_add_u32 s24, s68, s22
	s_addc_u32 s25, s69, s23
	s_and_b64 s[22:23], s[4:5], exec
	s_cselect_b32 s21, s25, s15
	s_cselect_b32 s62, s24, s14
	s_ashr_i32 s19, s18, 31
	s_lshl_b64 s[22:23], s[18:19], 21
	s_add_u32 s22, s86, s22
	s_addc_u32 s23, s87, s23
	s_and_b64 s[28:29], s[4:5], exec
	s_cselect_b32 s19, s23, s27
	s_cselect_b32 s63, s22, s26
	v_lshl_add_u64 v[146:147], s[14:15], 0, v[138:139]
	v_lshl_add_u64 v[148:149], s[14:15], 0, v[140:141]
	s_mov_b32 s64, -2
	s_mov_b64 s[26:27], 0
	.p2align 6
